# NSA selected-loop PV: six V^T fragment reads prefetched with counted lgkmcnt waits
# speedup vs baseline: 1.0452x; 1.0005x over previous
; #define LAS __attribute__((address_space(3)))
; __device__ __forceinline__ float sum32(float v) { auto rr = __builtin_amdgcn_permlane32_swap(__float_as_uint(v), __float_as_uint(v), false, false); return __uint_as_float(rr[0]) + __uint_as_float(rr[1]); }
; __device__ __forceinline__ float max32(float v) { auto rr = __builtin_amdgcn_permlane32_swap(__float_as_uint(v), __float_as_uint(v), false, false); return fmaxf(__uint_as_float(rr[0]), __uint_as_float(rr[1])); }
; #define MFMA32(a, b, c) __builtin_amdgcn_mfma_f32_32x32x16_bf16((a), (b), (c), 0, 0, 0)
; #define EXP2(x) __builtin_amdgcn_exp2f(x)
; __device__ __forceinline__ void attn_block_full(const bf16x8 (&qf)[4], f32x16& o0, f32x16& o1, float& m, float& l, LAS const unsigned char* ksb, LAS const unsigned char* vtb, int r, int hh, float b0, float sl) {
;     f32x16 s0, s1;
; #pragma unroll
;     for (int i = 0; i < 16; ++i) { s0[i] = 0.f; s1[i] = 0.f; }
;     bf16x8 ka[4], kb2[4];
; #pragma unroll
;     for (int s = 0; s < 4; ++s) { ka[s] = *(LAS const bf16x8*)(ksb + r * KSB + (16 * s + 8 * hh) * 2); kb2[s] = *(LAS const bf16x8*)(ksb + (32 + r) * KSB + (16 * s + 8 * hh) * 2); }
;     __builtin_amdgcn_s_setprio(1);
; #pragma unroll
;     for (int s = 0; s < 4; ++s) { s0 = MFMA32(ka[s], qf[s], s0); s1 = MFMA32(kb2[s], qf[s], s1); }
;     __builtin_amdgcn_s_setprio(0);
;     __builtin_amdgcn_sched_barrier(0);
; #pragma unroll
;     for (int i = 0; i < 16; ++i) { const float c = (float)((i & 3) + 8 * (i >> 2)); s0[i] = fmaf(sl, c, s0[i]); s1[i] = fmaf(sl, c + 32.f, s1[i]); }
;     float mloc = fmaxf(s0[0], s1[0]);
; #pragma unroll
;     for (int i = 1; i < 16; ++i) mloc = fmaxf(mloc, fmaxf(s0[i], s1[i]));
;     mloc = max32(mloc + b0);
;     const float mnew = fmaxf(m, mloc), msafe = mnew == -INFINITY ? 0.f : mnew, corr = EXP2(m - msafe), c0 = b0 - msafe;
;     float psum = 0.f;
; #pragma unroll
;     for (int i = 0; i < 16; ++i) { s0[i] = EXP2(s0[i] + c0); s1[i] = EXP2(s1[i] + c0); psum += s0[i] + s1[i]; }
;     psum = sum32(psum);
;     l = l * corr + psum; m = mnew;
.LBB0_1298:
	s_and_b64 vcc, exec, s[8:9]
	s_cbranch_vccz .LBB0_1300
	s_nop 6
	ds_read_b128 v[34:37], v115
	ds_read_b128 v[116:119], v115 offset:32
	ds_read_b128 v[38:41], v115 offset:4608
	ds_read_b128 v[120:123], v115 offset:4640
	ds_read_b128 v[124:127], v115 offset:64
	ds_read_b128 v[128:131], v115 offset:96
	ds_read_b128 v[186:189], v115 offset:4672
	ds_read_b128 v[190:193], v115 offset:4704
	v_or_b32_e32 v0, s24, v133
	v_sub_u32_e32 v0, v102, v0
	v_cvt_f32_i32_e32 v0, v0
	v_mul_f32_e64 v0, -v105, v0
	v_cndmask_b32_e64 v0, v215, v0, s[0:1]
	s_setprio 1
	s_waitcnt lgkmcnt(7)
	v_mfma_f32_32x32x16_bf16 v[50:65], v[34:37], v[74:77], 0
	s_waitcnt lgkmcnt(5)
	v_mfma_f32_32x32x16_bf16 v[34:49], v[38:41], v[74:77], 0
	v_mfma_f32_32x32x16_bf16 v[50:65], v[116:119], v[70:73], v[50:65]
	s_waitcnt lgkmcnt(4)
	v_mfma_f32_32x32x16_bf16 v[34:49], v[120:123], v[70:73], v[34:49]
	s_waitcnt lgkmcnt(3)
	v_mfma_f32_32x32x16_bf16 v[50:65], v[124:127], v[66:69], v[50:65]
	s_waitcnt lgkmcnt(1)
	v_mfma_f32_32x32x16_bf16 v[34:49], v[186:189], v[66:69], v[34:49]
	v_mfma_f32_32x32x16_bf16 v[50:65], v[128:131], v[78:81], v[50:65]
	s_waitcnt lgkmcnt(0)
	v_mfma_f32_32x32x16_bf16 v[34:49], v[190:193], v[78:81], v[34:49]
	s_setprio 0
	s_nop 8
	v_add_f32_e32 v51, v105, v51
	s_nop 0
	v_fmamk_f32 v35, v105, 0x42040000, v35
	v_fma_f32 v50, 0, v105, v50
	v_fmamk_f32 v34, v105, 0x42000000, v34
	v_fma_f32 v52, 2.0, v105, v52
	v_fmamk_f32 v36, v105, 0x42080000, v36
	v_fmamk_f32 v53, v105, 0x40400000, v53
	v_fmamk_f32 v37, v105, 0x420c0000, v37
	v_max_f32_e32 v115, v51, v35
	v_fmamk_f32 v54, v105, 0x41000000, v54
	v_fmamk_f32 v38, v105, 0x42200000, v38
	v_fmamk_f32 v55, v105, 0x41100000, v55
	v_fmamk_f32 v39, v105, 0x42240000, v39
	v_max3_f32 v115, v50, v34, v115
	v_max_f32_e32 v116, v52, v36
	v_max_f32_e32 v117, v53, v37
	v_fmamk_f32 v56, v105, 0x41200000, v56
	v_fmamk_f32 v40, v105, 0x42280000, v40
	v_fmamk_f32 v57, v105, 0x41300000, v57
	v_fmamk_f32 v41, v105, 0x422c0000, v41
	v_max3_f32 v115, v115, v116, v117
	v_max_f32_e32 v116, v54, v38
	v_max_f32_e32 v117, v55, v39
	v_fmamk_f32 v58, v105, 0x41800000, v58
	v_fmamk_f32 v42, v105, 0x42400000, v42
	v_fmamk_f32 v59, v105, 0x41880000, v59
	v_fmamk_f32 v43, v105, 0x42440000, v43
	v_max3_f32 v115, v115, v116, v117
	v_max_f32_e32 v116, v56, v40
	v_max_f32_e32 v117, v57, v41
	v_fmamk_f32 v60, v105, 0x41900000, v60
	v_fmamk_f32 v44, v105, 0x42480000, v44
	v_fmamk_f32 v61, v105, 0x41980000, v61
	v_fmamk_f32 v45, v105, 0x424c0000, v45
	v_max3_f32 v115, v115, v116, v117
	v_max_f32_e32 v116, v58, v42
	v_max_f32_e32 v117, v59, v43
	v_fmamk_f32 v62, v105, 0x41c00000, v62
	v_fmamk_f32 v46, v105, 0x42600000, v46
	v_fmamk_f32 v63, v105, 0x41c80000, v63
	v_fmamk_f32 v47, v105, 0x42640000, v47
	v_max3_f32 v115, v115, v116, v117
	v_max_f32_e32 v116, v60, v44
	v_max_f32_e32 v117, v61, v45
	v_fmamk_f32 v64, v105, 0x41d00000, v64
	v_fmamk_f32 v48, v105, 0x42680000, v48
	v_fmac_f32_e32 v65, 0x41d80000, v105
	v_fmac_f32_e32 v49, 0x426c0000, v105
	v_max3_f32 v115, v115, v116, v117
	v_max_f32_e32 v116, v62, v46
	v_max_f32_e32 v117, v63, v47
	v_max3_f32 v115, v115, v116, v117
	v_max_f32_e32 v116, v64, v48
	v_max_f32_e32 v117, v65, v49
	v_max3_f32 v115, v115, v116, v117
	v_add_f32_e32 v115, v0, v115
	v_mov_b32_e32 v116, v115
	s_nop 1
	v_permlane32_swap_b32_e32 v115, v116
	v_max3_f32 v185, v114, v115, v116
	v_cmp_neq_f32_e32 vcc, s34, v185
	s_nop 1
	v_cndmask_b32_e32 v115, 0, v185, vcc
	v_sub_f32_e32 v195, v0, v115
	v_add_f32_e32 v0, v50, v195
	v_exp_f32_e32 v196, v0
	v_add_f32_e32 v0, v34, v195
	v_exp_f32_e32 v197, v0
	v_add_f32_e32 v0, v51, v195
	v_exp_f32_e32 v128, v0
	v_add_f32_e32 v0, v35, v195
	v_exp_f32_e32 v0, v0
	v_add_f32_e32 v129, v196, v197
	v_sub_f32_e32 v194, v114, v115
	v_exp_f32_e32 v50, v194
	v_pk_add_f32 v[34:35], v[128:129], v[0:1]
	s_nop 0
	v_pk_add_f32 v[114:115], v[34:35], v[34:35] op_sel_hi:[0,1]
	v_add_f32_e32 v34, v52, v195
	v_exp_f32_e32 v129, v34
	v_add_f32_e32 v34, v36, v195
	v_exp_f32_e32 v198, v34
	v_add_f32_e32 v34, v53, v195
	v_exp_f32_e32 v140, v34
	v_add_f32_e32 v34, v37, v195
	v_exp_f32_e32 v114, v34
	v_add_f32_e32 v141, v129, v198
	v_pk_mul_f32 v[20:21], v[20:21], v[50:51] op_sel_hi:[1,0]
	v_pk_mul_f32 v[4:5], v[4:5], v[50:51] op_sel_hi:[1,0]
	v_pk_add_f32 v[34:35], v[140:141], v[114:115]
	s_nop 0
	v_pk_add_f32 v[118:119], v[34:35], v[34:35] op_sel_hi:[0,1]
	v_add_f32_e32 v34, v54, v195
	v_exp_f32_e32 v115, v34
	v_add_f32_e32 v34, v38, v195
	v_exp_f32_e32 v141, v34
	v_add_f32_e32 v34, v55, v195
	v_exp_f32_e32 v146, v34
	v_add_f32_e32 v34, v39, v195
	v_exp_f32_e32 v118, v34
	v_add_f32_e32 v147, v115, v141
	v_pk_mul_f32 v[22:23], v[22:23], v[50:51] op_sel_hi:[1,0]
; #define LAS __attribute__((address_space(3)))
; __device__ __forceinline__ float sum32(float v) { auto rr = __builtin_amdgcn_permlane32_swap(__float_as_uint(v), __float_as_uint(v), false, false); return __uint_as_float(rr[0]) + __uint_as_float(rr[1]); }
; #define EXP2(x) __builtin_amdgcn_exp2f(x)
; __device__ __forceinline__ void pv_accum(const f32x16& s0, const f32x16& s1, f32x16& o0, f32x16& o1, LAS const unsigned char* vtb, int r, int hh) {
;     __builtin_amdgcn_s_setprio(1);
; #pragma unroll
;     for (int kt = 0; kt < 2; ++kt)
; #pragma unroll
;         for (int sp = 0; sp < 2; ++sp) { u32x4 w;
;             if (kt == 0) { w.x = cvtpk(s0[8 * sp], s0[8 * sp + 1]); w.y = cvtpk(s0[8 * sp + 2], s0[8 * sp + 3]); w.z = cvtpk(s0[8 * sp + 4], s0[8 * sp + 5]); w.w = cvtpk(s0[8 * sp + 6], s0[8 * sp + 7]); }
;             else         { w.x = cvtpk(s1[8 * sp], s1[8 * sp + 1]); w.y = cvtpk(s1[8 * sp + 2], s1[8 * sp + 3]); w.z = cvtpk(s1[8 * sp + 4], s1[8 * sp + 5]); w.w = cvtpk(s1[8 * sp + 6], s1[8 * sp + 7]); }
;             const bf16x8 pb = __builtin_bit_cast(bf16x8, w); const int ko = 32 * kt + 16 * sp + 4 * hh;
;             { const s16x4 lo = *(LAS const s16x4*)(vtb + r * VTB + ko * 2), hi = *(LAS const s16x4*)(vtb + r * VTB + (ko + 8) * 2);
;               o0 = MFMA32(__builtin_shufflevector(lo, hi, 0, 1, 2, 3, 4, 5, 6, 7), pb, o0); }
;             { const s16x4 lo = *(LAS const s16x4*)(vtb + (32 + r) * VTB + ko * 2), hi = *(LAS const s16x4*)(vtb + (32 + r) * VTB + (ko + 8) * 2);
;               o1 = MFMA32(__builtin_shufflevector(lo, hi, 0, 1, 2, 3, 4, 5, 6, 7), pb, o1); } }
;     __builtin_amdgcn_s_setprio(0);
; __device__ __forceinline__ void attn_block_full(const bf16x8 (&qf)[4], f32x16& o0, f32x16& o1, float& m, float& l, LAS const unsigned char* ksb, LAS const unsigned char* vtb, int r, int hh, float b0, float sl) {
;     ...
;     const float mnew = fmaxf(m, mloc), msafe = mnew == -INFINITY ? 0.f : mnew, corr = EXP2(m - msafe), c0 = b0 - msafe;
;     float psum = 0.f;
; #pragma unroll
;     for (int i = 0; i < 16; ++i) { s0[i] = EXP2(s0[i] + c0); s1[i] = EXP2(s1[i] + c0); psum += s0[i] + s1[i]; }
;     psum = sum32(psum);
;     l = l * corr + psum; m = mnew;
; #pragma unroll
;     for (int i = 0; i < 16; ++i) { o0[i] *= corr; o1[i] *= corr; }
;     __builtin_amdgcn_sched_barrier(0);
;     pv_accum(s0, s1, o0, o1, vtb, r, hh);
	v_pk_mul_f32 v[6:7], v[6:7], v[50:51] op_sel_hi:[1,0]
	v_pk_add_f32 v[34:35], v[146:147], v[118:119]
	s_nop 0
	v_pk_add_f32 v[122:123], v[34:35], v[34:35] op_sel_hi:[0,1]
	v_add_f32_e32 v34, v56, v195
	v_exp_f32_e32 v119, v34
	v_add_f32_e32 v34, v40, v195
	v_exp_f32_e32 v147, v34
	v_add_f32_e32 v34, v57, v195
	v_exp_f32_e32 v186, v34
	v_add_f32_e32 v34, v41, v195
	v_exp_f32_e32 v122, v34
	v_add_f32_e32 v187, v119, v147
	v_pk_mul_f32 v[24:25], v[24:25], v[50:51] op_sel_hi:[1,0]
	v_pk_mul_f32 v[8:9], v[8:9], v[50:51] op_sel_hi:[1,0]
	v_pk_add_f32 v[34:35], v[186:187], v[122:123]
	s_nop 0
	v_pk_add_f32 v[116:117], v[34:35], v[34:35] op_sel_hi:[0,1]
	v_add_f32_e32 v34, v58, v195
	v_exp_f32_e32 v123, v34
	v_add_f32_e32 v34, v42, v195
	v_exp_f32_e32 v187, v34
	v_add_f32_e32 v34, v59, v195
	v_exp_f32_e32 v130, v34
	v_add_f32_e32 v34, v43, v195
	v_exp_f32_e32 v116, v34
	v_add_f32_e32 v131, v123, v187
	v_pk_mul_f32 v[26:27], v[26:27], v[50:51] op_sel_hi:[1,0]
	v_pk_mul_f32 v[10:11], v[10:11], v[50:51] op_sel_hi:[1,0]
	v_pk_add_f32 v[34:35], v[130:131], v[116:117]
	s_nop 0
	v_pk_add_f32 v[120:121], v[34:35], v[34:35] op_sel_hi:[0,1]
	v_add_f32_e32 v34, v60, v195
	v_exp_f32_e32 v131, v34
	v_add_f32_e32 v34, v44, v195
	v_exp_f32_e32 v199, v34
	v_add_f32_e32 v34, v61, v195
	v_exp_f32_e32 v188, v34
	v_add_f32_e32 v34, v45, v195
	v_exp_f32_e32 v120, v34
	v_add_f32_e32 v189, v131, v199
	v_pk_mul_f32 v[28:29], v[28:29], v[50:51] op_sel_hi:[1,0]
	v_pk_mul_f32 v[12:13], v[12:13], v[50:51] op_sel_hi:[1,0]
	v_pk_add_f32 v[34:35], v[188:189], v[120:121]
	s_nop 0
	v_pk_add_f32 v[124:125], v[34:35], v[34:35] op_sel_hi:[0,1]
	v_add_f32_e32 v34, v62, v195
	v_exp_f32_e32 v121, v34
	v_add_f32_e32 v34, v46, v195
	v_exp_f32_e32 v189, v34
	v_add_f32_e32 v34, v63, v195
	v_exp_f32_e32 v190, v34
	v_add_f32_e32 v34, v47, v195
	v_exp_f32_e32 v124, v34
	v_add_f32_e32 v191, v121, v189
	v_pk_mul_f32 v[30:31], v[30:31], v[50:51] op_sel_hi:[1,0]
	v_pk_mul_f32 v[14:15], v[14:15], v[50:51] op_sel_hi:[1,0]
	v_pk_add_f32 v[34:35], v[190:191], v[124:125]
	s_nop 0
	v_pk_add_f32 v[126:127], v[34:35], v[34:35] op_sel_hi:[0,1]
	v_add_f32_e32 v34, v64, v195
	v_exp_f32_e32 v125, v34
	v_add_f32_e32 v34, v48, v195
	v_exp_f32_e32 v191, v34
	v_add_f32_e32 v34, v65, v195
	v_exp_f32_e32 v192, v34
	v_add_f32_e32 v34, v49, v195
	v_exp_f32_e32 v126, v34
	v_add_f32_e32 v193, v125, v191
	v_pk_mul_f32 v[32:33], v[32:33], v[50:51] op_sel_hi:[1,0]
	v_pk_mul_f32 v[16:17], v[16:17], v[50:51] op_sel_hi:[1,0]
	v_pk_add_f32 v[34:35], v[192:193], v[126:127]
	s_nop 0
	v_pk_add_f32 v[34:35], v[34:35], v[34:35] op_sel:[0,1] op_sel_hi:[1,0]
	s_nop 0
	v_mov_b32_e32 v35, v34
	s_nop 1
	v_permlane32_swap_b32_e32 v34, v35
	v_add_f32_e32 v117, v34, v35
	v_fmac_f32_e32 v117, v184, v50
	v_pk_mul_f32 v[18:19], v[18:19], v[50:51] op_sel_hi:[1,0]
	v_pk_mul_f32 v[2:3], v[2:3], v[50:51] op_sel_hi:[1,0]
	s_setprio 1
	v_add3_u32 v46, s44, v151, v132
	v_add_u32_e32 v47, 0x4800, v46
	v_add_u32_e32 v46, 0x5800, v46
	ds_read2_b64 v[38:41], v47 offset1:2
	ds_read2_b64 v[48:51], v46 offset0:32 offset1:34
	ds_read2_b64 v[52:55], v46 offset0:36 offset1:38
	ds_read2_b64 v[42:45], v47 offset0:4 offset1:6
	ds_read2_b64 v[56:59], v47 offset0:8 offset1:10
	ds_read2_b64 v[60:63], v46 offset0:40 offset1:42
	v_cvt_pk_bf16_f32 v34, v196, v128
	v_cvt_pk_bf16_f32 v35, v129, v140
	v_cvt_pk_bf16_f32 v36, v115, v146
	v_cvt_pk_bf16_f32 v37, v119, v186
	s_waitcnt lgkmcnt(5)
	s_nop 0
	v_mfma_f32_32x32x16_bf16 v[18:33], v[38:41], v[34:37], v[18:33]
	ds_read2_b64 v[38:41], v47 offset0:12 offset1:14
	s_waitcnt lgkmcnt(5)
	v_mfma_f32_32x32x16_bf16 v[2:17], v[48:51], v[34:37], v[2:17]
	ds_read2_b64 v[48:51], v46 offset0:44 offset1:46
	v_cvt_pk_bf16_f32 v34, v123, v130
	v_cvt_pk_bf16_f32 v35, v131, v188
	v_cvt_pk_bf16_f32 v36, v121, v190
	v_cvt_pk_bf16_f32 v37, v125, v192
	s_waitcnt lgkmcnt(5)
	s_nop 0
	v_mfma_f32_32x32x16_bf16 v[2:17], v[52:55], v[34:37], v[2:17]
	s_waitcnt lgkmcnt(4)
	v_mfma_f32_32x32x16_bf16 v[18:33], v[42:45], v[34:37], v[18:33]
	v_cvt_pk_bf16_f32 v34, v197, v0
	v_cvt_pk_bf16_f32 v35, v198, v114
	v_cvt_pk_bf16_f32 v36, v141, v118
	v_cvt_pk_bf16_f32 v37, v147, v122
	s_waitcnt lgkmcnt(3)
	s_nop 0
	v_mfma_f32_32x32x16_bf16 v[18:33], v[56:59], v[34:37], v[18:33]
	s_waitcnt lgkmcnt(2)
	v_mfma_f32_32x32x16_bf16 v[2:17], v[60:63], v[34:37], v[2:17]
	v_cvt_pk_bf16_f32 v34, v187, v116
	v_cvt_pk_bf16_f32 v35, v199, v120
	v_cvt_pk_bf16_f32 v36, v189, v124
	v_cvt_pk_bf16_f32 v37, v191, v126
	s_waitcnt lgkmcnt(1)
	s_nop 0
	v_mfma_f32_32x32x16_bf16 v[18:33], v[38:41], v[34:37], v[18:33]
	s_waitcnt lgkmcnt(0)
	v_mfma_f32_32x32x16_bf16 v[2:17], v[48:51], v[34:37], v[2:17]
